# combine: second pair's partial-O loads hoisted (one round trip per iteration); prologue x->bf16: eight row loads issued together
# speedup vs baseline: 1.0473x; 1.0017x over previous
.LBB0_30:
	v_ashrrev_i32_e32 v1, 31, v0
	s_waitcnt lgkmcnt(0)
	v_lshlrev_b64 v[24:25], 13, v[0:1]
	v_lshl_add_u64 v[52:53], s[64:65], 0, v[24:25]
	v_lshl_add_u64 v[36:37], v[52:53], 0, v[2:3]
	v_lshlrev_b64 v[28:29], 12, v[0:1]
	v_lshl_add_u64 v[56:57], v[6:7], 0, v[28:29]
	v_lshl_add_u64 v[40:41], v[52:53], 0, v[8:9]
	v_lshl_add_u64 v[44:45], v[52:53], 0, v[10:11]
	v_lshl_add_u64 v[48:49], v[52:53], 0, v[12:13]
	v_lshl_add_u64 v[52:53], v[52:53], 0, v[14:15]
	global_load_dwordx4 v[24:27], v[36:37], off
	global_load_dwordx4 v[28:31], v[36:37], off offset:1024
	global_load_dwordx4 v[32:35], v[36:37], off offset:2048
	global_load_dwordx4 v[36:39], v[36:37], off offset:3072
	global_load_dwordx4 v[40:43], v[40:41], off
	global_load_dwordx4 v[44:47], v[44:45], off
	global_load_dwordx4 v[48:51], v[48:49], off
	global_load_dwordx4 v[52:55], v[52:53], off
	s_waitcnt vmcnt(7)
	v_cvt_pk_bf16_f32 v60, v24, v25
	v_cvt_pk_bf16_f32 v61, v26, v27
	global_store_dwordx2 v[56:57], v[60:61], off
	s_waitcnt vmcnt(7)
	v_cvt_pk_bf16_f32 v62, v28, v29
	v_cvt_pk_bf16_f32 v63, v30, v31
	global_store_dwordx2 v[56:57], v[62:63], off offset:512
	s_waitcnt vmcnt(7)
	v_cvt_pk_bf16_f32 v60, v32, v33
	v_cvt_pk_bf16_f32 v61, v34, v35
	global_store_dwordx2 v[56:57], v[60:61], off offset:1024
	s_waitcnt vmcnt(7)
	v_cvt_pk_bf16_f32 v62, v36, v37
	v_cvt_pk_bf16_f32 v63, v38, v39
	global_store_dwordx2 v[56:57], v[62:63], off offset:1536
	s_waitcnt vmcnt(7)
	v_cvt_pk_bf16_f32 v60, v40, v41
	v_cvt_pk_bf16_f32 v61, v42, v43
	global_store_dwordx2 v[56:57], v[60:61], off offset:2048
	s_waitcnt vmcnt(7)
	v_cvt_pk_bf16_f32 v62, v44, v45
	v_cvt_pk_bf16_f32 v63, v46, v47
	global_store_dwordx2 v[56:57], v[62:63], off offset:2560
	s_waitcnt vmcnt(7)
	v_cvt_pk_bf16_f32 v60, v48, v49
	v_cvt_pk_bf16_f32 v61, v50, v51
	global_store_dwordx2 v[56:57], v[60:61], off offset:3072
	v_cmp_lt_i32_e64 s[0:1], v18, v17
	v_mul_f32_e32 v25, v25, v25
	v_mul_f32_e32 v27, v27, v27
	v_fmac_f32_e32 v25, v24, v24
	v_fmac_f32_e32 v27, v26, v26
	v_add_f32_e32 v24, v25, v27
	v_mul_f32_e32 v25, v29, v29
	v_mul_f32_e32 v26, v31, v31
	v_fmac_f32_e32 v25, v28, v28
	v_fmac_f32_e32 v26, v30, v30
	v_add_f32_e32 v25, v25, v26
	v_add_f32_e32 v24, v24, v25
	v_mul_f32_e32 v25, v33, v33
	v_mul_f32_e32 v26, v35, v35
	v_fmac_f32_e32 v25, v32, v32
	v_fmac_f32_e32 v26, v34, v34
	v_add_f32_e32 v25, v25, v26
	v_add_f32_e32 v24, v24, v25
	v_mul_f32_e32 v25, v37, v37
	v_mul_f32_e32 v26, v39, v39
	v_fmac_f32_e32 v25, v36, v36
	v_fmac_f32_e32 v26, v38, v38
	v_add_f32_e32 v25, v25, v26
	v_add_f32_e32 v24, v24, v25
	v_mul_f32_e32 v25, v41, v41
	v_mul_f32_e32 v26, v43, v43
	v_fmac_f32_e32 v25, v40, v40
	v_fmac_f32_e32 v26, v42, v42
	v_add_f32_e32 v25, v25, v26
	v_add_f32_e32 v24, v24, v25
	v_mul_f32_e32 v25, v45, v45
	v_mul_f32_e32 v26, v47, v47
	v_fmac_f32_e32 v25, v44, v44
	v_fmac_f32_e32 v26, v46, v46
	v_add_f32_e32 v25, v25, v26
	v_add_f32_e32 v24, v24, v25
	v_mul_f32_e32 v25, v49, v49
	v_mul_f32_e32 v26, v51, v51
	v_fmac_f32_e32 v25, v48, v48
	v_fmac_f32_e32 v26, v50, v50
	v_add_f32_e32 v25, v25, v26
	v_add_f32_e32 v24, v24, v25
	s_waitcnt vmcnt(0)
	v_mul_f32_e32 v25, v53, v53
	v_mul_f32_e32 v26, v55, v55
	v_fmac_f32_e32 v25, v52, v52
	v_fmac_f32_e32 v26, v54, v54
	v_cndmask_b32_e64 v58, v16, v18, s[0:1]
	v_add_f32_e32 v25, v25, v26
	v_lshlrev_b32_e32 v58, 2, v58
	v_add_f32_e32 v24, v24, v25
	ds_bpermute_b32 v25, v58, v24
	v_cmp_lt_i32_e64 s[0:1], v19, v17
	s_waitcnt lgkmcnt(0)
	v_add_f32_e32 v24, v24, v25
	v_cndmask_b32_e64 v26, v16, v19, s[0:1]
	v_lshlrev_b32_e32 v26, 2, v26
	ds_bpermute_b32 v25, v26, v24
	v_cmp_lt_i32_e64 s[0:1], v20, v17
	s_waitcnt lgkmcnt(0)
	v_add_f32_e32 v24, v24, v25
	v_cndmask_b32_e64 v26, v16, v20, s[0:1]
	v_lshlrev_b32_e32 v26, 2, v26
	ds_bpermute_b32 v25, v26, v24
	v_cmp_lt_i32_e64 s[0:1], v21, v17
	s_waitcnt lgkmcnt(0)
	v_add_f32_e32 v24, v24, v25
	v_cndmask_b32_e64 v26, v16, v21, s[0:1]
	v_lshlrev_b32_e32 v26, 2, v26
	ds_bpermute_b32 v25, v26, v24
	v_cmp_lt_i32_e64 s[0:1], v22, v17
	s_waitcnt lgkmcnt(0)
	v_add_f32_e32 v24, v24, v25
	v_cndmask_b32_e64 v26, v16, v22, s[0:1]
	v_lshlrev_b32_e32 v26, 2, v26
	ds_bpermute_b32 v25, v26, v24
	v_cmp_lt_i32_e64 s[0:1], v23, v17
	s_waitcnt lgkmcnt(0)
	v_add_f32_e32 v24, v24, v25
	v_cndmask_b32_e64 v26, v16, v23, s[0:1]
	v_lshlrev_b32_e32 v25, 2, v26
	ds_bpermute_b32 v25, v25, v24
	v_cvt_pk_bf16_f32 v26, v52, v53
	v_cvt_pk_bf16_f32 v27, v54, v55
	global_store_dwordx2 v[56:57], v[26:27], off offset:3584
	s_and_saveexec_b64 s[0:1], vcc
	s_cbranch_execz .LBB0_29
	v_lshlrev_b64 v[26:27], 7, v[0:1]
	s_waitcnt lgkmcnt(0)
	v_add_f32_e32 v1, v24, v25
	v_lshl_add_u64 v[26:27], v[4:5], 0, v[26:27]
	v_cndmask_b32_e64 v1, 0, v1, s[4:5]
	global_store_dword v[26:27], v1, off
	s_branch .LBB0_29

.LBB0_1422:
	v_add_u32_e32 v43, s17, v26
	s_mov_b32 s0, 0x10000
	v_cmp_gt_i32_e64 s[38:39], s0, v43
	v_ashrrev_i32_e32 v27, 12, v26
	s_movk_i32 s18, 0xfff
	v_cndmask_b32_e64 v47, v26, v43, s[38:39]
	v_ashrrev_i32_e32 v0, 12, v47
	v_bfi_b32 v2, -8, v0, v47
	v_ashrrev_i32_e32 v3, 31, v2
	v_ashrrev_i32_e32 v46, 3, v47
	v_lshlrev_b64 v[2:3], 12, v[2:3]
	v_readlane_b32 s0, v253, 23
	s_waitcnt vmcnt(0)
	v_bfi_b32 v28, -8, v27, v26
	v_and_or_b32 v2, v46, s18, v2
	v_readlane_b32 s1, v253, 24
	v_ashrrev_i32_e32 v29, 31, v28
	v_readlane_b32 s8, v253, 28
	v_lshl_add_u64 v[4:5], v[2:3], 2, s[0:1]
	v_lshlrev_b64 v[34:35], 12, v[28:29]
	v_ashrrev_i32_e32 v48, 3, v26
	global_load_dword v54, v[4:5], off
	v_lshlrev_b64 v[4:5], 5, v[2:3]
	v_readlane_b32 s9, v253, 29
	v_lshlrev_b64 v[2:3], 10, v[2:3]
	v_and_or_b32 v34, v48, s18, v34
	v_lshl_add_u64 v[4:5], s[8:9], 0, v[4:5]
	v_lshl_add_u64 v[2:3], v[44:45], 0, v[2:3]
	v_and_b32_e32 v0, 7, v26
	v_lshl_add_u64 v[26:27], v[34:35], 2, s[0:1]
	global_load_dwordx4 v[18:21], v[4:5], off offset:16
	global_load_dwordx4 v[22:25], v[4:5], off
	global_load_dwordx4 v[14:17], v[2:3], off
	global_load_dwordx4 v[10:13], v[2:3], off offset:256
	global_load_dwordx4 v[6:9], v[2:3], off offset:512
	s_nop 0
	global_load_dwordx4 v[2:5], v[2:3], off offset:768
	v_lshlrev_b32_e32 v0, 8, v0
	global_load_dword v36, v[26:27], off
	v_lshlrev_b64 v[26:27], 5, v[34:35]
	v_lshl_add_u64 v[30:31], s[8:9], 0, v[26:27]
	global_load_dwordx4 v[26:29], v[30:31], off offset:16
	s_nop 0
	global_load_dwordx4 v[30:33], v[30:31], off
	v_lshlrev_b64 v[64:65], 10, v[34:35]
	v_lshl_add_u64 v[64:65], v[44:45], 0, v[64:65]
	global_load_dwordx4 v[68:71], v[64:65], off
	global_load_dwordx4 v[72:75], v[64:65], off offset:256
	global_load_dwordx4 v[76:79], v[64:65], off offset:512
	global_load_dwordx4 v[80:83], v[64:65], off offset:768
	s_waitcnt vmcnt(6)
	v_cmp_eq_u32_e32 vcc, 0, v36
	v_bcnt_u32_b32 v36, v36, 0
	v_cmp_lt_u32_e64 s[40:41], 2, v36
	v_cmp_lt_u32_e64 s[42:43], 1, v36
	s_waitcnt vmcnt(5)
	v_max_f32_e32 v37, v28, v28
	v_cndmask_b32_e64 v26, v239, v26, s[40:41]
	v_max_f32_e32 v36, v26, v26
	s_waitcnt vmcnt(4)
	v_cndmask_b32_e32 v30, v30, v239, vcc
	v_cndmask_b32_e64 v32, v239, v32, s[42:43]
	v_max_f32_e32 v36, v36, v37
	v_max3_f32 v36, v30, v32, v36
	v_sub_f32_e32 v30, v30, v36
	v_exp_f32_e32 v30, v30
	v_sub_f32_e32 v26, v26, v36
	v_exp_f32_e32 v26, v26
	v_mul_f32_e32 v55, v31, v30
	v_fma_f32 v30, v31, v30, 0
	v_sub_f32_e32 v31, v32, v36
	v_exp_f32_e32 v31, v31
	v_cndmask_b32_e64 v30, v30, 0, vcc
	v_mul_f32_e32 v57, v27, v26
	v_cndmask_b32_e64 v26, 0, v57, s[40:41]
	v_mul_f32_e32 v56, v33, v31
	v_cndmask_b32_e64 v31, 0, v56, s[42:43]
	v_add_f32_e32 v30, v31, v30
	v_add_f32_e32 v49, v26, v30
	v_sub_f32_e32 v26, v28, v36
	v_exp_f32_e32 v26, v26
	s_nop 0
	v_mul_f32_e32 v58, v29, v26
	v_fmac_f32_e32 v49, v29, v26
	v_lshlrev_b64 v[26:27], 10, v[34:35]
	v_lshl_add_u64 v[38:39], v[44:45], 0, v[26:27]
	s_waitcnt vmcnt(0)
	v_mov_b32_e32 v26, v68
	v_mov_b32_e32 v27, v69
	v_mov_b32_e32 v28, v70
	v_mov_b32_e32 v29, v71
	s_waitcnt vmcnt(0)
	v_and_b32_e32 v30, 0xffff0000, v29
	v_fma_f32 v30, v55, v30, 0
	v_cndmask_b32_e64 v34, v30, 0, vcc
	v_mov_b32_e32 v30, v72
	v_mov_b32_e32 v31, v73
	v_mov_b32_e32 v32, v74
	v_mov_b32_e32 v33, v75
	s_waitcnt vmcnt(0)
	v_and_b32_e32 v35, 0xffff0000, v33
	v_mul_f32_e32 v35, v56, v35
	v_cndmask_b32_e64 v35, 0, v35, s[42:43]
	v_add_f32_e32 v40, v35, v34
	v_mov_b32_e32 v34, v76
	v_mov_b32_e32 v35, v77
	v_mov_b32_e32 v36, v78
	v_mov_b32_e32 v37, v79
	v_lshlrev_b32_e32 v52, 16, v32
	v_and_b32_e32 v32, 0xffff0000, v32
	v_mul_f32_e32 v32, v56, v32
	v_cndmask_b32_e64 v32, 0, v32, s[42:43]
	v_mul_f32_e32 v52, v56, v52
	v_cndmask_b32_e64 v52, 0, v52, s[42:43]
	s_waitcnt vmcnt(0)
	v_and_b32_e32 v41, 0xffff0000, v37
	v_mul_f32_e32 v41, v57, v41
	v_cndmask_b32_e64 v41, 0, v41, s[40:41]
	v_add_f32_e32 v51, v41, v40
	v_mov_b32_e32 v38, v80
	v_mov_b32_e32 v39, v81
	v_mov_b32_e32 v40, v82
	v_mov_b32_e32 v41, v83
	s_waitcnt vmcnt(0)
	v_and_b32_e32 v50, 0xffff0000, v41
	v_fmac_f32_e32 v51, v58, v50
	v_lshlrev_b32_e32 v50, 16, v28
	v_and_b32_e32 v28, 0xffff0000, v28
	v_fma_f32 v28, v55, v28, 0
	v_cndmask_b32_e64 v28, v28, 0, vcc
	v_add_f32_e32 v28, v32, v28
	v_and_b32_e32 v32, 0xffff0000, v36
	v_mul_f32_e32 v32, v57, v32
	v_cndmask_b32_e64 v32, 0, v32, s[40:41]
	v_add_f32_e32 v53, v32, v28
	v_and_b32_e32 v28, 0xffff0000, v40
	v_fma_f32 v50, v55, v50, 0
	v_fmac_f32_e32 v53, v58, v28
	v_lshlrev_b32_e32 v28, 16, v29
	v_lshlrev_b32_e32 v29, 16, v33
	v_cndmask_b32_e64 v50, v50, 0, vcc
	v_fma_f32 v28, v55, v28, 0
	v_mul_f32_e32 v29, v56, v29
	v_add_f32_e32 v50, v52, v50
	v_lshlrev_b32_e32 v52, 16, v36
	v_cndmask_b32_e64 v28, v28, 0, vcc
	v_cndmask_b32_e64 v29, 0, v29, s[42:43]
	v_mul_f32_e32 v52, v57, v52
	v_add_f32_e32 v28, v29, v28
	v_lshlrev_b32_e32 v29, 16, v37
	v_cndmask_b32_e64 v52, 0, v52, s[40:41]
	v_mul_f32_e32 v29, v57, v29
	v_add_f32_e32 v52, v52, v50
	v_lshlrev_b32_e32 v50, 16, v40
	v_cndmask_b32_e64 v29, 0, v29, s[40:41]
	v_fmac_f32_e32 v52, v58, v50
	v_add_f32_e32 v50, v29, v28
	v_lshlrev_b32_e32 v28, 16, v41
	v_fmac_f32_e32 v50, v58, v28
	v_and_b32_e32 v28, 0xffff0000, v27
	v_and_b32_e32 v29, 0xffff0000, v31
	v_fma_f32 v28, v55, v28, 0
	v_mul_f32_e32 v29, v56, v29
	v_cndmask_b32_e64 v28, v28, 0, vcc
	v_cndmask_b32_e64 v29, 0, v29, s[42:43]
	v_add_f32_e32 v28, v29, v28
	v_and_b32_e32 v29, 0xffff0000, v35
	v_mul_f32_e32 v29, v57, v29
	v_cndmask_b32_e64 v29, 0, v29, s[40:41]
	v_add_f32_e32 v29, v29, v28
	v_and_b32_e32 v28, 0xffff0000, v39
	v_fmac_f32_e32 v29, v58, v28
	v_lshlrev_b32_e32 v28, 16, v26
	v_lshlrev_b32_e32 v32, 16, v30
	v_fma_f32 v28, v55, v28, 0
	v_mul_f32_e32 v32, v56, v32
	v_cndmask_b32_e64 v28, v28, 0, vcc
	v_cndmask_b32_e64 v32, 0, v32, s[42:43]
	v_add_f32_e32 v28, v32, v28
	v_lshlrev_b32_e32 v32, 16, v34
	v_mul_f32_e32 v32, v57, v32
	v_cndmask_b32_e64 v32, 0, v32, s[40:41]
	v_add_f32_e32 v32, v32, v28
	v_lshlrev_b32_e32 v28, 16, v38
	v_fmac_f32_e32 v32, v58, v28
	v_and_b32_e32 v26, 0xffff0000, v26
	v_and_b32_e32 v28, 0xffff0000, v30
	v_fma_f32 v26, v55, v26, 0
	v_mul_f32_e32 v28, v56, v28
	v_cndmask_b32_e64 v26, v26, 0, vcc
	v_cndmask_b32_e64 v28, 0, v28, s[42:43]
	v_add_f32_e32 v26, v28, v26
	v_and_b32_e32 v28, 0xffff0000, v34
	v_mul_f32_e32 v28, v57, v28
	v_cndmask_b32_e64 v28, 0, v28, s[40:41]
	v_add_f32_e32 v33, v28, v26
	v_and_b32_e32 v26, 0xffff0000, v38
	v_fmac_f32_e32 v33, v58, v26
	v_lshlrev_b32_e32 v26, 16, v27
	v_lshlrev_b32_e32 v27, 16, v31
	v_fma_f32 v26, v55, v26, 0
	v_mul_f32_e32 v27, v56, v27
	v_cndmask_b32_e64 v26, v26, 0, vcc
	v_cndmask_b32_e64 v27, 0, v27, s[42:43]
	v_add_f32_e32 v26, v27, v26
	v_lshlrev_b32_e32 v27, 16, v35
	v_mul_f32_e32 v27, v57, v27
	v_cndmask_b32_e64 v27, 0, v27, s[40:41]
	v_add_f32_e32 v28, v27, v26
	v_lshlrev_b32_e32 v26, 16, v39
	v_fmac_f32_e32 v28, v58, v26
	v_div_scale_f32 v26, s[0:1], v49, v49, 1.0
	v_rcp_f32_e32 v27, v26
	s_nop 0
	v_fma_f32 v30, -v26, v27, 1.0
	v_fmac_f32_e32 v27, v30, v27
	v_div_scale_f32 v30, vcc, 1.0, v49, 1.0
	v_mul_f32_e32 v31, v30, v27
	v_fma_f32 v34, -v26, v31, v30
	v_fmac_f32_e32 v31, v34, v27
	v_fma_f32 v26, -v26, v31, v30
	v_div_fmas_f32 v26, v26, v27, v31
	v_div_fixup_f32 v26, v26, v49, 1.0
	v_pk_mul_f32 v[30:31], v[26:27], v[32:33] op_sel_hi:[0,1]
	v_ashrrev_i32_e32 v49, 31, v48
	v_pk_mul_f32 v[28:29], v[26:27], v[28:29] op_sel_hi:[0,1]
	v_pk_mul_f32 v[32:33], v[26:27], v[50:51] op_sel_hi:[0,1]
	v_pk_mul_f32 v[34:35], v[26:27], v[52:53] op_sel_hi:[0,1]
	v_cvt_pk_bf16_f32 v26, v30, v31
	v_lshlrev_b64 v[30:31], 12, v[48:49]
	v_lshl_add_u64 v[30:31], s[92:93], 0, v[30:31]
	v_lshl_add_u64 v[30:31], v[30:31], 0, v[0:1]
	v_lshlrev_b32_e32 v0, 1, v42
	v_lshl_add_u64 v[30:31], v[30:31], 0, v[0:1]
	v_add_co_u32_e32 v30, vcc, 0x28d81000, v30
	v_cvt_pk_bf16_f32 v27, v28, v29
	v_cvt_pk_bf16_f32 v28, v34, v35
	v_cvt_pk_bf16_f32 v29, v32, v33
	s_nop 1
	v_addc_co_u32_e32 v31, vcc, 0, v31, vcc
	global_store_dwordx4 v[30:31], v[26:29], off offset:3072
	s_and_saveexec_b64 s[8:9], s[38:39]
	s_cbranch_execz .LBB0_1421
	v_bcnt_u32_b32 v26, v54, 0
	v_cmp_lt_u32_e32 vcc, 2, v26
	v_cmp_eq_u32_e64 s[0:1], 0, v54
	v_cmp_lt_u32_e64 s[38:39], 1, v26
	v_cndmask_b32_e32 v18, v239, v18, vcc
	v_max_f32_e32 v26, v18, v18
	v_max_f32_e32 v27, v20, v20
	v_cndmask_b32_e64 v22, v22, v239, s[0:1]
	v_cndmask_b32_e64 v24, v239, v24, s[38:39]
	v_max_f32_e32 v26, v26, v27
	v_max3_f32 v26, v22, v24, v26
	v_sub_f32_e32 v22, v22, v26
	v_sub_f32_e32 v24, v24, v26
	v_exp_f32_e32 v22, v22
	v_exp_f32_e32 v24, v24
	v_sub_f32_e32 v18, v18, v26
	v_exp_f32_e32 v18, v18
	v_mul_f32_e32 v28, v23, v22
	v_fma_f32 v22, v23, v22, 0
	v_mul_f32_e32 v23, v25, v24
	v_cndmask_b32_e64 v22, v22, 0, s[0:1]
	v_cndmask_b32_e64 v24, 0, v23, s[38:39]
	v_add_f32_e32 v22, v24, v22
	v_mul_f32_e32 v24, v19, v18
	v_cndmask_b32_e32 v18, 0, v24, vcc
	v_add_f32_e32 v22, v18, v22
	v_and_b32_e32 v18, 0xffff0000, v17
	v_and_b32_e32 v19, 0xffff0000, v13
	v_sub_f32_e32 v20, v20, v26
	v_fma_f32 v18, v28, v18, 0
	v_mul_f32_e32 v19, v23, v19
	v_exp_f32_e32 v20, v20
	v_cndmask_b32_e64 v18, v18, 0, s[0:1]
	v_cndmask_b32_e64 v19, 0, v19, s[38:39]
	v_add_f32_e32 v18, v19, v18
	v_and_b32_e32 v19, 0xffff0000, v9
	v_mul_f32_e32 v19, v24, v19
	v_cndmask_b32_e32 v19, 0, v19, vcc
	v_mul_f32_e32 v25, v21, v20
	v_add_f32_e32 v19, v19, v18
	v_and_b32_e32 v18, 0xffff0000, v5
	v_fmac_f32_e32 v22, v21, v20
	v_fmac_f32_e32 v19, v25, v18
	v_lshlrev_b32_e32 v18, 16, v16
	v_lshlrev_b32_e32 v20, 16, v12
	v_fma_f32 v18, v28, v18, 0
	v_mul_f32_e32 v20, v23, v20
	v_cndmask_b32_e64 v18, v18, 0, s[0:1]
	v_cndmask_b32_e64 v20, 0, v20, s[38:39]
	v_and_b32_e32 v16, 0xffff0000, v16
	v_and_b32_e32 v12, 0xffff0000, v12
	v_add_f32_e32 v18, v20, v18
	v_lshlrev_b32_e32 v20, 16, v8
	v_fma_f32 v16, v28, v16, 0
	v_mul_f32_e32 v12, v23, v12
	v_and_b32_e32 v8, 0xffff0000, v8
	v_mul_f32_e32 v20, v24, v20
	v_cndmask_b32_e64 v16, v16, 0, s[0:1]
	v_cndmask_b32_e64 v12, 0, v12, s[38:39]
	v_mul_f32_e32 v8, v24, v8
	v_cndmask_b32_e32 v20, 0, v20, vcc
	v_add_f32_e32 v12, v12, v16
	v_cndmask_b32_e32 v8, 0, v8, vcc
	v_add_f32_e32 v20, v20, v18
	v_lshlrev_b32_e32 v18, 16, v4
	v_add_f32_e32 v21, v8, v12
	v_and_b32_e32 v4, 0xffff0000, v4
	v_fmac_f32_e32 v21, v25, v4
	v_lshlrev_b32_e32 v4, 16, v17
	v_lshlrev_b32_e32 v8, 16, v13
	v_fma_f32 v4, v28, v4, 0
	v_mul_f32_e32 v8, v23, v8
	v_cndmask_b32_e64 v4, v4, 0, s[0:1]
	v_cndmask_b32_e64 v8, 0, v8, s[38:39]
	v_add_f32_e32 v4, v8, v4
	v_lshlrev_b32_e32 v8, 16, v9
	v_mul_f32_e32 v8, v24, v8
	v_cndmask_b32_e32 v8, 0, v8, vcc
	v_fmac_f32_e32 v20, v25, v18
	v_add_f32_e32 v18, v8, v4
	v_lshlrev_b32_e32 v4, 16, v5
	v_fmac_f32_e32 v18, v25, v4
	v_and_b32_e32 v4, 0xffff0000, v15
	v_and_b32_e32 v5, 0xffff0000, v11
	v_fma_f32 v4, v28, v4, 0
	v_mul_f32_e32 v5, v23, v5
	v_cndmask_b32_e64 v4, v4, 0, s[0:1]
	v_cndmask_b32_e64 v5, 0, v5, s[38:39]
	v_add_f32_e32 v4, v5, v4
	v_and_b32_e32 v5, 0xffff0000, v7
	v_mul_f32_e32 v5, v24, v5
	v_cndmask_b32_e32 v5, 0, v5, vcc
	v_add_f32_e32 v5, v5, v4
	v_and_b32_e32 v4, 0xffff0000, v3
	v_fmac_f32_e32 v5, v25, v4
	v_lshlrev_b32_e32 v4, 16, v14
	v_lshlrev_b32_e32 v8, 16, v10
	v_fma_f32 v4, v28, v4, 0
	v_mul_f32_e32 v8, v23, v8
	v_cndmask_b32_e64 v4, v4, 0, s[0:1]
	v_cndmask_b32_e64 v8, 0, v8, s[38:39]
	v_add_f32_e32 v4, v8, v4
	v_lshlrev_b32_e32 v8, 16, v6
	v_mul_f32_e32 v8, v24, v8
	v_cndmask_b32_e32 v8, 0, v8, vcc
	v_add_f32_e32 v8, v8, v4
	v_lshlrev_b32_e32 v4, 16, v2
	v_fmac_f32_e32 v8, v25, v4
	v_and_b32_e32 v4, 0xffff0000, v14
	v_and_b32_e32 v9, 0xffff0000, v10
	v_fma_f32 v4, v28, v4, 0
	v_mul_f32_e32 v9, v23, v9
	v_and_b32_e32 v6, 0xffff0000, v6
	v_cndmask_b32_e64 v4, v4, 0, s[0:1]
	v_cndmask_b32_e64 v9, 0, v9, s[38:39]
	v_mul_f32_e32 v6, v24, v6
	v_add_f32_e32 v4, v9, v4
	v_cndmask_b32_e32 v6, 0, v6, vcc
	v_add_f32_e32 v9, v6, v4
	v_and_b32_e32 v2, 0xffff0000, v2
	v_fmac_f32_e32 v9, v25, v2
	v_lshlrev_b32_e32 v2, 16, v15
	v_lshlrev_b32_e32 v4, 16, v11
	v_fma_f32 v2, v28, v2, 0
	v_mul_f32_e32 v4, v23, v4
	v_cndmask_b32_e64 v2, v2, 0, s[0:1]
	v_cndmask_b32_e64 v4, 0, v4, s[38:39]
	v_div_scale_f32 v6, s[0:1], v22, v22, 1.0
	v_add_f32_e32 v2, v4, v2
	v_lshlrev_b32_e32 v4, 16, v7
	v_rcp_f32_e32 v7, v6
	v_mul_f32_e32 v4, v24, v4
	v_cndmask_b32_e32 v4, 0, v4, vcc
	v_add_f32_e32 v4, v4, v2
	v_lshlrev_b32_e32 v2, 16, v3
	v_fmac_f32_e32 v4, v25, v2
	v_fma_f32 v2, -v6, v7, 1.0
	v_fmac_f32_e32 v7, v2, v7
	v_div_scale_f32 v2, vcc, 1.0, v22, 1.0
	v_mul_f32_e32 v3, v2, v7
	v_fma_f32 v10, -v6, v3, v2
	v_fmac_f32_e32 v3, v10, v7
	v_fma_f32 v2, -v6, v3, v2
	v_div_fmas_f32 v2, v2, v7, v3
	v_div_fixup_f32 v2, v2, v22, 1.0
	v_and_b32_e32 v27, 7, v47
	v_pk_mul_f32 v[6:7], v[2:3], v[8:9] op_sel_hi:[0,1]
	v_ashrrev_i32_e32 v47, 31, v46
	v_pk_mul_f32 v[4:5], v[2:3], v[4:5] op_sel_hi:[0,1]
	v_pk_mul_f32 v[8:9], v[2:3], v[18:19] op_sel_hi:[0,1]
	v_pk_mul_f32 v[10:11], v[2:3], v[20:21] op_sel_hi:[0,1]
	v_cvt_pk_bf16_f32 v2, v6, v7
	v_lshlrev_b64 v[6:7], 12, v[46:47]
	v_cvt_pk_bf16_f32 v3, v4, v5
	v_cvt_pk_bf16_f32 v4, v10, v11
	v_cvt_pk_bf16_f32 v5, v8, v9
	v_lshl_add_u64 v[6:7], s[92:93], 0, v[6:7]
	v_lshlrev_b32_e32 v8, 8, v27
	v_mov_b32_e32 v9, v1
	v_lshl_add_u64 v[6:7], v[6:7], 0, v[8:9]
	v_lshl_add_u64 v[6:7], v[6:7], 0, v[0:1]
	v_add_co_u32_e32 v6, vcc, 0x28d81000, v6
	s_nop 1
	v_addc_co_u32_e32 v7, vcc, 0, v7, vcc
	global_store_dwordx4 v[6:7], v[2:5], off offset:3072
	s_branch .LBB0_1421
